# attention fast path output stage: the 4 softmax-denominator LDS reads issued before the last PV MFMAs, packed f32 mul + bf16 pack for row pairs (16 VALU per 8 outputs -> 8), the 4 staging read-backs i
# baseline (speedup 1.0000x reference)
; #define LAS __attribute__((address_space(3)))
; #define LDS_WAIT() asm volatile("s_waitcnt lgkmcnt(0)" ::: "memory")
; __device__ __forceinline__ unsigned pk2(float lo, float hi) { f32x2_t v = {lo, hi}; bf16x2_t b = __builtin_convertvector(v, bf16x2_t); return __builtin_bit_cast(unsigned, b); }
; __device__ __forceinline__ void attn_phase(int wave_s, LAS unsigned char* lds, const bf16* QKV, bf16* O, const float* qg, const float* kg, const float* sinks, const float* bt) {
;     ...
; #pragma unroll
;             for (int kk = 0; kk < 5; ++kk) { const bool blk_ok = (nb > 0) || (c + kk >= 4);
;                 if (blk_ok) {
; #pragma unroll
;                     for (int ks = 0; ks < 2; ++ks) { v4u pw; pw.x = pk2(p[kk][8 * ks + 0], p[kk][8 * ks + 1]); pw.y = pk2(p[kk][8 * ks + 2], p[kk][8 * ks + 3]);
;                         pw.z = pk2(p[kk][8 * ks + 4], p[kk][8 * ks + 5]); pw.w = pk2(p[kk][8 * ks + 6], p[kk][8 * ks + 7]);
;                         const bf16x8 pa = __builtin_bit_cast(bf16x8, pw);
; #pragma unroll
;                         for (int db = 0; db < 2; ++db) { const LAS bf16* vp = Vt + (db * 32 + r32) * VT_STRIDE + 32 * (c + kk) + 16 * ks + 4 * hi;
;                             const v2u lo = *(const LAS v2u*)vp, hh = *(const LAS v2u*)(vp + 8); const v4u vv = (v4u){lo.x, lo.y, hh.x, hh.y};
;                             o[db] = __builtin_amdgcn_mfma_f32_32x32x16_bf16(pa, __builtin_bit_cast(bf16x8, vv), o[db], 0, 0, 0); } } } }
;             LDS_WAIT();
;             LAS bf16* stg = (LAS bf16*)(lds + ALDS_OST) + wid * 2048;
; #pragma unroll
;             for (int rq = 0; rq < 4; ++rq) { const f32x4 iv = *(const LAS f32x4*)(wsf + 8 * rq + 4 * hi);
.Lfa_nod:
	s_or_b64 exec, exec, s[2:3]
	v_cvt_pk_bf16_f32 v112, v80, v81
	v_cvt_pk_bf16_f32 v113, v82, v83
	v_cvt_pk_bf16_f32 v114, v84, v85
	v_cvt_pk_bf16_f32 v115, v86, v87
	v_cvt_pk_bf16_f32 v116, v88, v89
	v_cvt_pk_bf16_f32 v117, v90, v91
	v_cvt_pk_bf16_f32 v118, v92, v93
	v_cvt_pk_bf16_f32 v119, v94, v95
	v_cvt_pk_bf16_f32 v228, v16, v17
	v_cvt_pk_bf16_f32 v229, v18, v19
	v_cvt_pk_bf16_f32 v230, v20, v21
	v_cvt_pk_bf16_f32 v231, v22, v23
	v_cvt_pk_bf16_f32 v240, v24, v25
	v_cvt_pk_bf16_f32 v241, v26, v27
	v_cvt_pk_bf16_f32 v242, v28, v29
	v_cvt_pk_bf16_f32 v243, v30, v31
	s_waitcnt lgkmcnt(4)
	v_mfma_f32_32x32x16_bf16 v[2:17], v[228:231], v[196:199], 0
	v_mfma_f32_32x32x16_bf16 v[80:95], v[228:231], v[200:203], 0
	v_mfma_f32_32x32x16_bf16 v[2:17], v[240:243], v[204:207], v[2:17]
	v_mfma_f32_32x32x16_bf16 v[80:95], v[240:243], v[208:211], v[80:95]
	ds_read2_b64 v[196:199], v156 offset0:16 offset1:18
	ds_read2_b64 v[200:203], v244 offset0:48 offset1:50
	ds_read2_b64 v[204:207], v156 offset0:20 offset1:22
	ds_read2_b64 v[208:211], v244 offset0:52 offset1:54
	v_cvt_pk_bf16_f32 v228, v32, v33
	v_cvt_pk_bf16_f32 v229, v34, v35
	v_cvt_pk_bf16_f32 v230, v36, v37
	v_cvt_pk_bf16_f32 v231, v38, v39
	v_cvt_pk_bf16_f32 v240, v40, v41
	v_cvt_pk_bf16_f32 v241, v42, v43
	v_cvt_pk_bf16_f32 v242, v44, v45
	v_cvt_pk_bf16_f32 v243, v46, v47
	s_waitcnt lgkmcnt(4)
	v_mfma_f32_32x32x16_bf16 v[2:17], v[228:231], v[212:215], v[2:17]
	v_mfma_f32_32x32x16_bf16 v[80:95], v[228:231], v[216:219], v[80:95]
	v_mfma_f32_32x32x16_bf16 v[2:17], v[240:243], v[220:223], v[2:17]
	v_mfma_f32_32x32x16_bf16 v[80:95], v[240:243], v[224:227], v[80:95]
	ds_read2_b64 v[212:215], v156 offset0:24 offset1:26
	ds_read2_b64 v[216:219], v244 offset0:56 offset1:58
	ds_read2_b64 v[220:223], v156 offset0:28 offset1:30
	ds_read2_b64 v[224:227], v244 offset0:60 offset1:62
	v_cvt_pk_bf16_f32 v228, v48, v49
	v_cvt_pk_bf16_f32 v229, v50, v51
	v_cvt_pk_bf16_f32 v230, v52, v53
	v_cvt_pk_bf16_f32 v231, v54, v55
	v_cvt_pk_bf16_f32 v240, v56, v57
	v_cvt_pk_bf16_f32 v241, v58, v59
	v_cvt_pk_bf16_f32 v242, v60, v61
	v_cvt_pk_bf16_f32 v243, v62, v63
	s_waitcnt lgkmcnt(4)
	v_mfma_f32_32x32x16_bf16 v[2:17], v[228:231], v[196:199], v[2:17]
	v_mfma_f32_32x32x16_bf16 v[80:95], v[228:231], v[200:203], v[80:95]
	v_mfma_f32_32x32x16_bf16 v[2:17], v[240:243], v[204:207], v[2:17]
	v_mfma_f32_32x32x16_bf16 v[80:95], v[240:243], v[208:211], v[80:95]
	ds_read2_b64 v[196:199], v156 offset0:32 offset1:34
	ds_read2_b64 v[200:203], v244 offset0:64 offset1:66
	ds_read2_b64 v[204:207], v156 offset0:36 offset1:38
	ds_read2_b64 v[208:211], v244 offset0:68 offset1:70
	v_cvt_pk_bf16_f32 v228, v64, v65
	v_cvt_pk_bf16_f32 v229, v66, v67
	v_cvt_pk_bf16_f32 v230, v68, v69
	v_cvt_pk_bf16_f32 v231, v70, v71
	v_cvt_pk_bf16_f32 v240, v72, v73
	v_cvt_pk_bf16_f32 v241, v74, v75
	v_cvt_pk_bf16_f32 v242, v76, v77
	v_cvt_pk_bf16_f32 v243, v78, v79
	ds_read_b128 v[18:21], v147
	ds_read_b128 v[22:25], v147 offset:32
	ds_read_b128 v[26:29], v147 offset:64
	ds_read_b128 v[30:33], v147 offset:96
	s_waitcnt lgkmcnt(8)
	v_mfma_f32_32x32x16_bf16 v[2:17], v[228:231], v[212:215], v[2:17]
	v_mfma_f32_32x32x16_bf16 v[80:95], v[228:231], v[216:219], v[80:95]
	v_mfma_f32_32x32x16_bf16 v[2:17], v[240:243], v[220:223], v[2:17]
	v_mfma_f32_32x32x16_bf16 v[80:95], v[240:243], v[224:227], v[80:95]
	s_waitcnt lgkmcnt(0)
; #define LAS __attribute__((address_space(3)))
; #define LDS_WAIT() asm volatile("s_waitcnt lgkmcnt(0)" ::: "memory")
; __device__ __forceinline__ unsigned pk2(float lo, float hi) { f32x2_t v = {lo, hi}; bf16x2_t b = __builtin_convertvector(v, bf16x2_t); return __builtin_bit_cast(unsigned, b); }
; __device__ __forceinline__ void attn_phase(int wave_s, LAS unsigned char* lds, const bf16* QKV, bf16* O, const float* qg, const float* kg, const float* sinks, const float* bt) {
;     ...
;             LDS_WAIT();
;             LAS bf16* stg = (LAS bf16*)(lds + ALDS_OST) + wid * 2048;
; #pragma unroll
;             for (int rq = 0; rq < 4; ++rq) { const f32x4 iv = *(const LAS f32x4*)(wsf + 8 * rq + 4 * hi);
; #pragma unroll
;                 for (int e = 0; e < 4; ++e) { const int r = 4 * rq + e, q = 8 * rq + 4 * hi + e; stg[q * 64 + r32] = (bf16)(pk2(o[0][r] * iv[e], 0.f) & 0xffffu); stg[q * 64 + 32 + r32] = (bf16)(pk2(o[1][r] * iv[e], 0.f) & 0xffffu); } }
;             LDS_WAIT();
;             bf16* Ow = O + ((size_t)b * SEQ + nb * 128 + 32 * c) * DM + h * HD;
; #pragma unroll
;             for (int i = 0; i < 4; ++i) { const int row = i * 8 + (lane >> 3), ch = lane & 7; const v4u v = *(const LAS v4u*)(stg + row * 64 + ch * 8); *(v4u*)(Ow + (size_t)row * DM + ch * 8) = v; }
	v_mfma_f32_32x32x16_bf16 v[2:17], v[112:115], v[196:199], v[2:17]
	v_mfma_f32_32x32x16_bf16 v[80:95], v[112:115], v[200:203], v[80:95]
	v_mfma_f32_32x32x16_bf16 v[2:17], v[116:119], v[204:207], v[2:17]
	v_mfma_f32_32x32x16_bf16 v[80:95], v[116:119], v[208:211], v[80:95]
	v_add_u32_e32 v157, 0x1200, v157
	v_add_u32_e32 v156, 64, v156
	s_mov_b32 s2, 0x1d400000
	s_nop 7
	s_nop 1
	v_pk_mul_f32 v[50:51], v[2:3], v[18:19]
	v_pk_mul_f32 v[52:53], v[80:81], v[18:19]
	v_pk_mul_f32 v[54:55], v[4:5], v[20:21]
	v_pk_mul_f32 v[56:57], v[82:83], v[20:21]
	v_cvt_pk_bf16_f32 v50, v50, v51
	v_cvt_pk_bf16_f32 v52, v52, v53
	v_cvt_pk_bf16_f32 v54, v54, v55
	v_cvt_pk_bf16_f32 v56, v56, v57
	ds_write_b16 v152, v50
	ds_write_b16_d16_hi v152, v50 offset:128
	ds_write_b16 v152, v52 offset:64
	ds_write_b16_d16_hi v152, v52 offset:192
	ds_write_b16 v152, v54 offset:256
	ds_write_b16_d16_hi v152, v54 offset:384
	ds_write_b16 v152, v56 offset:320
	ds_write_b16_d16_hi v152, v56 offset:448
	v_pk_mul_f32 v[58:59], v[6:7], v[22:23]
	v_pk_mul_f32 v[60:61], v[84:85], v[22:23]
	v_pk_mul_f32 v[62:63], v[8:9], v[24:25]
	v_pk_mul_f32 v[64:65], v[86:87], v[24:25]
	v_cvt_pk_bf16_f32 v58, v58, v59
	v_cvt_pk_bf16_f32 v60, v60, v61
	v_cvt_pk_bf16_f32 v62, v62, v63
	v_cvt_pk_bf16_f32 v64, v64, v65
	ds_write_b16 v152, v58 offset:1024
	ds_write_b16_d16_hi v152, v58 offset:1152
	ds_write_b16 v152, v60 offset:1088
	ds_write_b16_d16_hi v152, v60 offset:1216
	ds_write_b16 v152, v62 offset:1280
	ds_write_b16_d16_hi v152, v62 offset:1408
	ds_write_b16 v152, v64 offset:1344
	ds_write_b16_d16_hi v152, v64 offset:1472
	v_lshl_add_u64 v[6:7], v[140:141], 0, s[90:91]
	v_add_co_u32_e32 v8, vcc, s2, v6
	s_mov_b32 s2, 0x1d408000
	s_add_u32 s90, s90, 0x20000
	v_addc_co_u32_e32 v9, vcc, 0, v7, vcc
	s_addc_u32 s91, s91, 0
	v_pk_mul_f32 v[66:67], v[10:11], v[26:27]
	v_pk_mul_f32 v[68:69], v[88:89], v[26:27]
	v_pk_mul_f32 v[70:71], v[12:13], v[28:29]
	v_pk_mul_f32 v[72:73], v[90:91], v[28:29]
	v_cvt_pk_bf16_f32 v66, v66, v67
	v_cvt_pk_bf16_f32 v68, v68, v69
	v_cvt_pk_bf16_f32 v70, v70, v71
	v_cvt_pk_bf16_f32 v72, v72, v73
	ds_write_b16 v152, v66 offset:2048
	ds_write_b16_d16_hi v152, v66 offset:2176
	ds_write_b16 v152, v68 offset:2112
	ds_write_b16_d16_hi v152, v68 offset:2240
	ds_write_b16 v152, v70 offset:2304
	ds_write_b16_d16_hi v152, v70 offset:2432
	ds_write_b16 v152, v72 offset:2368
	ds_write_b16_d16_hi v152, v72 offset:2496
	v_pk_mul_f32 v[50:51], v[14:15], v[30:31]
	v_pk_mul_f32 v[52:53], v[92:93], v[30:31]
	v_pk_mul_f32 v[54:55], v[16:17], v[32:33]
	v_pk_mul_f32 v[56:57], v[94:95], v[32:33]
	v_cvt_pk_bf16_f32 v50, v50, v51
	v_cvt_pk_bf16_f32 v52, v52, v53
	v_cvt_pk_bf16_f32 v54, v54, v55
	v_cvt_pk_bf16_f32 v56, v56, v57
	ds_write_b16 v152, v50 offset:3072
	ds_write_b16_d16_hi v152, v50 offset:3200
	ds_write_b16 v152, v52 offset:3136
	ds_write_b16_d16_hi v152, v52 offset:3264
	ds_write_b16 v152, v54 offset:3328
	ds_write_b16_d16_hi v152, v54 offset:3456
	ds_write_b16 v152, v56 offset:3392
	ds_write_b16_d16_hi v152, v56 offset:3520
	v_add_u32_e32 v1, v148, v149
	s_waitcnt lgkmcnt(0)
	ds_read_b128 v[34:37], v1
	ds_read_b128 v[38:41], v153
	ds_read_b128 v[42:45], v154
	ds_read_b128 v[46:49], v155
	v_add_co_u32_e32 v10, vcc, s2, v6
	s_mov_b32 s2, 0x1d410000
	s_add_i32 s36, s36, 1
	v_addc_co_u32_e32 v11, vcc, 0, v7, vcc
	v_add_co_u32_e32 v12, vcc, s2, v6
	s_mov_b32 s2, 0x1d418000
	s_nop 0
	v_addc_co_u32_e32 v13, vcc, 0, v7, vcc
	v_add_co_u32_e32 v14, vcc, s2, v6
	s_mov_b64 s[2:3], 0x28000
	s_cmp_eq_u32 s90, 0x80000
	v_addc_co_u32_e32 v15, vcc, 0, v7, vcc
	v_lshl_add_u64 v[138:139], v[138:139], 0, s[2:3]
	s_waitcnt lgkmcnt(3)
	global_store_dwordx4 v[8:9], v[34:37], off
	s_waitcnt lgkmcnt(2)
	global_store_dwordx4 v[10:11], v[38:41], off
	s_waitcnt lgkmcnt(1)
	global_store_dwordx4 v[12:13], v[42:45], off
	s_waitcnt lgkmcnt(0)
	global_store_dwordx4 v[14:15], v[46:49], off
	s_waitcnt vmcnt(4)
	s_cbranch_scc0 .Lfa_top
	s_branch .LBB0_475
